# next-unit coordinates updated incrementally (row panel fixed, column panel +4) instead of full index decode in the three multi-unit GEMM phases
# baseline (speedup 1.0000x reference)
;     __host__ __device__ bool next(int i, Unit& u) const {
;         const long L = (long)i * G + c; if (L >= nwg) return false;
;         int wgid = (int)L; { const int q = nwg / NXCD, r = nwg % NXCD, xcd = wgid % NXCD, off = wgid / NXCD; wgid = (xcd < r ? xcd * (q + 1) : r * (q + 1) + (xcd - r) * q) + off; }
;         const int nig = WGM * nN, gid = wgid / nig, fm = gid * WGM, gsz = (nM - fm) < WGM ? (nM - fm) : WGM;
;         u.pm = fm + ((wgid % nig) % gsz); u.pn = (wgid % nig) / gsz; return true;
.LBB0_124:
	s_add_i32 s68, s68, 1
	s_mul_i32 s4, s68, s62
	s_mul_hi_u32 s5, s68, s60
	s_add_i32 s5, s5, s4
	s_mul_i32 s4, s68, s60
	s_add_u32 s12, s4, s2
	s_addc_u32 s13, s5, s33
	v_cmp_gt_i64_e32 vcc, s[12:13], v[144:145]
	v_cmp_lt_i64_e64 s[4:5], s[12:13], v[142:143]
	s_cbranch_vccnz .LBB0_126
	s_mov_b32 s72, s88
	s_add_i32 s70, s97, 4

;     __host__ __device__ bool next(int i, Unit& u) const {
;         const long L = (long)i * G + c; if (L >= nwg) return false;
;         int wgid = (int)L; { const int q = nwg / NXCD, r = nwg % NXCD, xcd = wgid % NXCD, off = wgid / NXCD; wgid = (xcd < r ? xcd * (q + 1) : r * (q + 1) + (xcd - r) * q) + off; }
;         const int nig = WGM * nN, gid = wgid / nig, fm = gid * WGM, gsz = (nM - fm) < WGM ? (nM - fm) : WGM;
;         u.pm = fm + ((wgid % nig) % gsz); u.pn = (wgid % nig) / gsz; return true;
.LBB0_396:
	s_add_i32 s35, s35, 1
	s_mul_i32 s8, s35, s62
	s_mul_hi_u32 s9, s35, s60
	s_add_i32 s9, s9, s8
	s_mul_i32 s8, s35, s60
	s_add_u32 s12, s8, s2
	s_addc_u32 s13, s9, s33
	v_cmp_gt_i64_e32 vcc, s[12:13], v[152:153]
	v_cmp_lt_i64_e64 s[8:9], s[12:13], v[150:151]
	s_cbranch_vccnz .LBB0_402
	s_mov_b32 s90, s46
	s_add_i32 s88, s94, 4

;     __host__ __device__ bool next(int i, Unit& u) const {
;         const long L = (long)i * G + c; if (L >= nwg) return false;
;         int wgid = (int)L; { const int q = nwg / NXCD, r = nwg % NXCD, xcd = wgid % NXCD, off = wgid / NXCD; wgid = (xcd < r ? xcd * (q + 1) : r * (q + 1) + (xcd - r) * q) + off; }
;         const int nig = WGM * nN, gid = wgid / nig, fm = gid * WGM, gsz = (nM - fm) < WGM ? (nM - fm) : WGM;
;         u.pm = fm + ((wgid % nig) % gsz); u.pn = (wgid % nig) / gsz; return true;
.LBB0_1022:
	s_add_i32 s34, s34, 1
	s_mul_i32 s1, s34, s62
	s_mul_hi_u32 s6, s34, s60
	s_add_i32 s6, s6, s1
	s_mul_i32 s1, s34, s60
	s_add_u32 s12, s1, s2
	s_addc_u32 s13, s6, s33
	v_cmp_gt_i64_e32 vcc, s[12:13], v[144:145]
	v_cmp_lt_i64_e64 s[6:7], s[12:13], v[142:143]
	s_cbranch_vccnz .LBB0_1024
	s_mov_b32 s18, s26
	s_add_i32 s0, s46, 4
